# v59 layout: v50 + 6 s_nop before the P2 K-loop + 3 at the scan exit (P5/P7/P8 at the same addresses as v56; P2, tail tile and scan 4 B earlier; probe table puts it ~4 us ahead of v56)
# speedup vs baseline: 1.0003x; 1.0003x over previous
; #define PG8_STAGE(bufoff, gbase, voff) do { _Pragma("unroll") for (int _i = 0; _i < 2; ++_i) \
;         __builtin_amdgcn_global_load_lds((const unsigned*)((const char*)(gbase) + (voff)[_i]), (PG8_LAS unsigned*)(lds + (bufoff) + ldsw + _i * 8192), 16, 0, 0); } while (0)
; #define PG8_LDA(dst, b, h) do { _Pragma("unroll") for (int m = 0; m < 4; ++m) _Pragma("unroll") for (int k = 0; k < 2; ++k) dst[m][k] = *(const PG8_LAS bf16x8*)(lds + PG8_SA(b, h) + aoff + m * 2048 + k * 1024); } while (0)
; #define PG8_LDB(dst, b, h) do { _Pragma("unroll") for (int n = 0; n < 2; ++n) _Pragma("unroll") for (int k = 0; k < 2; ++k) dst[n][k] = *(const PG8_LAS bf16x8*)(lds + PG8_SB(b, h) + boff + n * 2048 + k * 1024); } while (0)
; #define PG8_WAIT_V(n) asm volatile("s_waitcnt vmcnt(" #n ")" ::: "memory")
; #define PG8_WAIT_L(n) asm volatile("s_waitcnt lgkmcnt(" #n ")" ::: "memory")
; #define PG8_BAR __builtin_amdgcn_s_barrier()
; template <class Epi, class Sched, bool ALIGN_EPI = false, bool SP2 = false>
; __device__ __forceinline__ void gemm_phase(PG8_LAS unsigned char* lds, const Gemm g, const Sched& S, const Epi& E) {
;     ...
;         const bool has_next = S.next(ui + 1, nxt);
;         const char* nA = has_next ? (const char*)g.A + (size_t)nxt.pm * tstep : cA; const char* nB = has_next ? (const char*)g.Bt + (size_t)nxt.pn * tstep : cB;
;         for (int t = 0; t < nt; t += 2) {
;             const bool last = (t == nt - 2);
;             const char* a1 = cA + (size_t)(t + 1) * kstep;
;             const char* a2 = last ? nA : cA + (size_t)(t + 2) * kstep; const char* b2 = last ? nB : cB + (size_t)(t + 2) * kstep;
;             const char* a3 = a2 + kstep; const char* b3 = b2 + kstep;
;             if (last && has_next) S.a_ready(nxt);
;             if constexpr (SP2) {
;             PG8_LDB(B0, 0, 0); PG8_LDB(B1, 0, 1); PG8_SCHED; PG8_LDA(At, 0, 0); PG8_STAGE(PG8_SA(1, 1), a1 + hstep, voffA);
;             PG8_WAIT_V(8); PG8_WAIT_L(0); PG8_BAR; PG8_MMA(0, 0, At, B0); PG8_MMA(0, 1, At, B1); PG8_BAR; PG8_SCHED;
;     ...
; #pragma unroll
;         for (int a = 0; a < 2; ++a)
; #pragma unroll
;             for (int b = 0; b < 2; ++b)
; #pragma unroll
;                 for (int m = 0; m < 4; ++m)
; #pragma unroll
;                     for (int n = 0; n < 2; ++n) acc[a][b][m][n] = (f32x4){0.f, 0.f, 0.f, 0.f};
;         cur = nxt; cA = nA; cB = nB; ++ui;
.LBB0_182:
	s_ashr_i32 s39, s38, 31
	s_lshl_b64 s[10:11], s[38:39], 21
	s_add_u32 s70, s74, s10
	v_readlane_b32 s1, v247, 29
	s_addc_u32 s71, s1, s11
	s_and_b64 s[10:11], s[66:67], exec
	s_cselect_b32 s1, s71, s7
	s_cselect_b32 s12, s70, s6
	s_ashr_i32 s85, s84, 31
	s_lshl_b64 s[10:11], s[84:85], 21
	s_add_u32 s72, s36, s10
	s_addc_u32 s73, s37, s11
	s_and_b64 s[10:11], s[66:67], exec
	s_cselect_b32 s13, s73, s9
	s_cselect_b32 s14, s72, s8
	s_add_u32 s6, s6, 0x100080
	s_addc_u32 s7, s7, 0
	s_add_u32 s15, s8, 0x100
	v_mov_b32_e32 v2, 0
	s_addc_u32 s16, s9, 0
	s_mov_b32 s17, -2
	v_mov_b32_e32 v3, v2
	v_mov_b32_e32 v4, v2
	v_mov_b32_e32 v5, v2
	v_mov_b32_e32 v6, v2
	v_mov_b32_e32 v7, v2
	v_mov_b32_e32 v8, v2
	v_mov_b32_e32 v9, v2
	v_mov_b32_e32 v14, v2
	v_mov_b32_e32 v15, v2
	v_mov_b32_e32 v16, v2
	v_mov_b32_e32 v17, v2
	v_mov_b32_e32 v22, v2
	v_mov_b32_e32 v23, v2
	v_mov_b32_e32 v24, v2
	v_mov_b32_e32 v25, v2
	v_mov_b32_e32 v30, v2
	v_mov_b32_e32 v31, v2
	v_mov_b32_e32 v32, v2
	v_mov_b32_e32 v33, v2
	v_mov_b32_e32 v38, v2
	v_mov_b32_e32 v39, v2
	v_mov_b32_e32 v40, v2
	v_mov_b32_e32 v41, v2
	v_mov_b32_e32 v46, v2
	v_mov_b32_e32 v47, v2
	v_mov_b32_e32 v48, v2
	v_mov_b32_e32 v49, v2
	v_mov_b32_e32 v54, v2
	v_mov_b32_e32 v55, v2
	v_mov_b32_e32 v56, v2
	v_mov_b32_e32 v57, v2
	v_mov_b32_e32 v10, v2
	v_mov_b32_e32 v11, v2
	v_mov_b32_e32 v12, v2
	v_mov_b32_e32 v13, v2
	v_mov_b32_e32 v18, v2
	v_mov_b32_e32 v19, v2
	v_mov_b32_e32 v20, v2
	v_mov_b32_e32 v21, v2
	v_mov_b32_e32 v26, v2
	v_mov_b32_e32 v27, v2
	v_mov_b32_e32 v28, v2
	v_mov_b32_e32 v29, v2
	v_mov_b32_e32 v34, v2
	v_mov_b32_e32 v35, v2
	v_mov_b32_e32 v36, v2
	v_mov_b32_e32 v37, v2
	v_mov_b32_e32 v42, v2
	v_mov_b32_e32 v43, v2
	v_mov_b32_e32 v44, v2
	v_mov_b32_e32 v45, v2
	v_mov_b32_e32 v50, v2
	v_mov_b32_e32 v51, v2
	v_mov_b32_e32 v52, v2
	v_mov_b32_e32 v53, v2
	v_mov_b32_e32 v58, v2
	v_mov_b32_e32 v59, v2
	v_mov_b32_e32 v60, v2
	v_mov_b32_e32 v61, v2
	v_mov_b32_e32 v62, v2
	v_mov_b32_e32 v63, v2
	v_mov_b32_e32 v64, v2
	v_mov_b32_e32 v65, v2
	v_mov_b32_e32 v66, v2
	v_mov_b32_e32 v67, v2
	v_mov_b32_e32 v68, v2
	v_mov_b32_e32 v69, v2
	v_mov_b32_e32 v70, v2
	v_mov_b32_e32 v71, v2
	v_mov_b32_e32 v72, v2
	v_mov_b32_e32 v73, v2
	v_mov_b32_e32 v78, v2
	v_mov_b32_e32 v79, v2
	v_mov_b32_e32 v80, v2
	v_mov_b32_e32 v81, v2
	v_mov_b32_e32 v86, v2
	v_mov_b32_e32 v87, v2
	v_mov_b32_e32 v88, v2
	v_mov_b32_e32 v89, v2
	v_mov_b32_e32 v94, v2
	v_mov_b32_e32 v95, v2
	v_mov_b32_e32 v96, v2
	v_mov_b32_e32 v97, v2
	v_mov_b32_e32 v102, v2
	v_mov_b32_e32 v103, v2
	v_mov_b32_e32 v104, v2
	v_mov_b32_e32 v105, v2
	v_mov_b32_e32 v110, v2
	v_mov_b32_e32 v111, v2
	v_mov_b32_e32 v112, v2
	v_mov_b32_e32 v113, v2
	v_mov_b32_e32 v118, v2
	v_mov_b32_e32 v119, v2
	v_mov_b32_e32 v120, v2
	v_mov_b32_e32 v121, v2
	v_mov_b32_e32 v74, v2
	v_mov_b32_e32 v75, v2
	v_mov_b32_e32 v76, v2
	v_mov_b32_e32 v77, v2
	v_mov_b32_e32 v82, v2
	v_mov_b32_e32 v83, v2
	v_mov_b32_e32 v84, v2
	v_mov_b32_e32 v85, v2
	v_mov_b32_e32 v90, v2
	v_mov_b32_e32 v91, v2
	v_mov_b32_e32 v92, v2
	v_mov_b32_e32 v93, v2
	v_mov_b32_e32 v98, v2
	v_mov_b32_e32 v99, v2
	v_mov_b32_e32 v100, v2
	v_mov_b32_e32 v101, v2
	v_mov_b32_e32 v106, v2
	v_mov_b32_e32 v107, v2
	v_mov_b32_e32 v108, v2
	v_mov_b32_e32 v109, v2
	v_mov_b32_e32 v114, v2
	v_mov_b32_e32 v115, v2
	v_mov_b32_e32 v116, v2
	v_mov_b32_e32 v117, v2
	v_mov_b32_e32 v122, v2
	v_mov_b32_e32 v123, v2
	v_mov_b32_e32 v124, v2
	v_mov_b32_e32 v125, v2
	v_mov_b32_e32 v126, v2
	v_mov_b32_e32 v127, v2
	v_mov_b32_e32 v128, v2
	v_mov_b32_e32 v129, v2
	s_waitcnt lgkmcnt(0)
	s_nop 0
	s_nop 0
	s_nop 0
	s_nop 0
	s_nop 0
	s_nop 0
.LBB0_183:
	ds_read_b128 v[144:147], v186
	ds_read_b128 v[148:151], v186 offset:1024
	ds_read_b128 v[152:155], v186 offset:2048
	ds_read_b128 v[156:159], v186 offset:3072
	ds_read_b128 v[160:163], v187
	ds_read_b128 v[164:167], v187 offset:1024
	ds_read_b128 v[168:171], v187 offset:2048
	ds_read_b128 v[172:175], v187 offset:3072
	s_add_u32 s8, s6, 0xfff00080
	s_addc_u32 s9, s7, -1
	s_cmp_eq_u32 s17, 60
	s_cselect_b32 s11, s1, s9
	s_cselect_b32 s10, s12, s8
	s_cselect_b32 s9, s13, s16
	s_cselect_b32 s8, s14, s15
	v_lshl_add_u64 v[214:215], s[6:7], 0, v[140:141]
	s_add_i32 m0, s41, 0xc000
	ds_read_b128 v[176:179], v188
	ds_read_b128 v[190:193], v188 offset:1024
	ds_read_b128 v[194:197], v188 offset:2048
	ds_read_b128 v[198:201], v188 offset:3072
	ds_read_b128 v[202:205], v188 offset:4096
	ds_read_b128 v[206:209], v188 offset:5120
	ds_read_b128 v[210:213], v188 offset:6144
	ds_read_b128 v[218:221], v188 offset:7168
	global_load_lds_dwordx4 v[214:215], off
	v_lshl_add_u64 v[214:215], s[6:7], 0, v[142:143]
	s_add_i32 m0, s41, 0xe000
	s_nop 0
	global_load_lds_dwordx4 v[214:215], off
	s_waitcnt vmcnt(8)
	s_waitcnt lgkmcnt(0)
	s_setprio 1
	s_barrier
; #define PG8_STAGE(bufoff, gbase, voff) do { _Pragma("unroll") for (int _i = 0; _i < 2; ++_i) \
;         __builtin_amdgcn_global_load_lds((const unsigned*)((const char*)(gbase) + (voff)[_i]), (PG8_LAS unsigned*)(lds + (bufoff) + ldsw + _i * 8192), 16, 0, 0); } while (0)
; #define PG8_LDA(dst, b, h) do { _Pragma("unroll") for (int m = 0; m < 4; ++m) _Pragma("unroll") for (int k = 0; k < 2; ++k) dst[m][k] = *(const PG8_LAS bf16x8*)(lds + PG8_SA(b, h) + aoff + m * 2048 + k * 1024); } while (0)
; #define PG8_MMA(ai, bj, At, Bt) do { __builtin_amdgcn_s_setprio(1); _Pragma("unroll") for (int m = 0; m < 4; ++m) _Pragma("unroll") for (int n = 0; n < 2; ++n) _Pragma("unroll") for (int k = 0; k < 2; ++k) \
;         acc[ai][bj][m][n] = __builtin_amdgcn_mfma_f32_16x16x32_bf16(Bt[n][k], At[m][k], acc[ai][bj][m][n], 0, 0, 0); __builtin_amdgcn_s_setprio(0); } while (0)
; #define PG8_WAIT_V(n) asm volatile("s_waitcnt vmcnt(" #n ")" ::: "memory")
; #define PG8_WAIT_L(n) asm volatile("s_waitcnt lgkmcnt(" #n ")" ::: "memory")
; #define PG8_BAR __builtin_amdgcn_s_barrier()
; #define PG8_SCHED __builtin_amdgcn_sched_barrier(0)
; template <class Epi, class Sched, bool ALIGN_EPI = false, bool SP2 = false>
; __device__ __forceinline__ void gemm_phase(PG8_LAS unsigned char* lds, const Gemm g, const Sched& S, const Epi& E) {
;     ...
;             PG8_WAIT_V(8); PG8_WAIT_L(0); PG8_BAR; PG8_MMA(0, 0, At, B0); PG8_MMA(0, 1, At, B1); PG8_BAR; PG8_SCHED;
;             PG8_LDA(At, 0, 1); PG8_STAGE(PG8_SB(0, 0), b2, voffB); PG8_STAGE(PG8_SB(0, 1), b2 + hstep, voffB); PG8_STAGE(PG8_SA(0, 0), a2, voffA);
;             PG8_WAIT_V(8); PG8_WAIT_L(0); PG8_BAR; PG8_MMA(1, 0, At, B0); PG8_MMA(1, 1, At, B1); PG8_BAR; PG8_SCHED;
	v_mfma_f32_16x16x32_bf16 v[126:129], v[144:147], v[176:179], v[126:129]
	v_mfma_f32_16x16x32_bf16 v[122:125], v[152:155], v[176:179], v[122:125]
	v_mfma_f32_16x16x32_bf16 v[114:117], v[144:147], v[194:197], v[114:117]
	v_mfma_f32_16x16x32_bf16 v[106:109], v[152:155], v[194:197], v[106:109]
	v_mfma_f32_16x16x32_bf16 v[98:101], v[144:147], v[202:205], v[98:101]
	v_mfma_f32_16x16x32_bf16 v[90:93], v[152:155], v[202:205], v[90:93]
	v_mfma_f32_16x16x32_bf16 v[82:85], v[144:147], v[210:213], v[82:85]
	v_mfma_f32_16x16x32_bf16 v[74:77], v[152:155], v[210:213], v[74:77]
	v_mfma_f32_16x16x32_bf16 v[126:129], v[148:151], v[190:193], v[126:129]
	v_mfma_f32_16x16x32_bf16 v[122:125], v[156:159], v[190:193], v[122:125]
	v_mfma_f32_16x16x32_bf16 v[114:117], v[148:151], v[198:201], v[114:117]
	v_mfma_f32_16x16x32_bf16 v[106:109], v[156:159], v[198:201], v[106:109]
	v_mfma_f32_16x16x32_bf16 v[98:101], v[148:151], v[206:209], v[98:101]
	v_mfma_f32_16x16x32_bf16 v[90:93], v[156:159], v[206:209], v[90:93]
	v_mfma_f32_16x16x32_bf16 v[82:85], v[148:151], v[218:221], v[82:85]
	v_mfma_f32_16x16x32_bf16 v[74:77], v[156:159], v[218:221], v[74:77]
	s_setprio 0
	s_setprio 1
	v_mfma_f32_16x16x32_bf16 v[118:121], v[160:163], v[176:179], v[118:121]
	v_mfma_f32_16x16x32_bf16 v[110:113], v[168:171], v[176:179], v[110:113]
	v_mfma_f32_16x16x32_bf16 v[102:105], v[160:163], v[194:197], v[102:105]
	v_mfma_f32_16x16x32_bf16 v[94:97], v[168:171], v[194:197], v[94:97]
	v_mfma_f32_16x16x32_bf16 v[86:89], v[160:163], v[202:205], v[86:89]
	v_mfma_f32_16x16x32_bf16 v[78:81], v[168:171], v[202:205], v[78:81]
	v_mfma_f32_16x16x32_bf16 v[70:73], v[160:163], v[210:213], v[70:73]
	v_mfma_f32_16x16x32_bf16 v[66:69], v[168:171], v[210:213], v[66:69]
	v_mfma_f32_16x16x32_bf16 v[118:121], v[164:167], v[190:193], v[118:121]
	v_mfma_f32_16x16x32_bf16 v[110:113], v[172:175], v[190:193], v[110:113]
	v_mfma_f32_16x16x32_bf16 v[102:105], v[164:167], v[198:201], v[102:105]
	v_mfma_f32_16x16x32_bf16 v[94:97], v[172:175], v[198:201], v[94:97]
	v_mfma_f32_16x16x32_bf16 v[86:89], v[164:167], v[206:209], v[86:89]
	v_mfma_f32_16x16x32_bf16 v[78:81], v[172:175], v[206:209], v[78:81]
	v_mfma_f32_16x16x32_bf16 v[70:73], v[164:167], v[218:221], v[70:73]
	v_mfma_f32_16x16x32_bf16 v[66:69], v[172:175], v[218:221], v[66:69]
	s_barrier
	s_setprio 0
	s_add_i32 s18, s62, s5
	v_lshl_add_u64 v[214:215], s[8:9], 0, v[132:133]
	s_mov_b32 m0, s18
	ds_read_b128 v[176:179], v188 offset:16384
	ds_read_b128 v[190:193], v188 offset:17408
	ds_read_b128 v[194:197], v188 offset:18432
	ds_read_b128 v[198:201], v188 offset:19456
	ds_read_b128 v[202:205], v188 offset:20480
	ds_read_b128 v[206:209], v188 offset:21504
	ds_read_b128 v[210:213], v188 offset:22528
	ds_read_b128 v[218:221], v188 offset:23552
	global_load_lds_dwordx4 v[214:215], off
	s_add_i32 m0, s18, 0x2000
	s_add_u32 s18, s8, 0x100000
	v_lshl_add_u64 v[222:223], s[8:9], 0, v[136:137]
	s_addc_u32 s19, s9, 0
	s_add_i32 s20, s63, s5
	global_load_lds_dwordx4 v[222:223], off
	v_lshl_add_u64 v[224:225], s[18:19], 0, v[132:133]
	s_mov_b32 m0, s20
	v_lshl_add_u64 v[226:227], s[10:11], 0, v[134:135]
	global_load_lds_dwordx4 v[224:225], off
	v_lshl_add_u64 v[224:225], s[18:19], 0, v[136:137]
	s_add_i32 m0, s20, 0x2000
	s_nop 0
	global_load_lds_dwordx4 v[224:225], off
	v_lshl_add_u64 v[224:225], s[10:11], 0, v[130:131]
	s_mov_b32 m0, s41
	s_nop 0
	global_load_lds_dwordx4 v[224:225], off
	s_mov_b32 m0, s43
	s_nop 0
	global_load_lds_dwordx4 v[226:227], off
	s_waitcnt vmcnt(8)
	s_waitcnt lgkmcnt(0)
	s_setprio 1
	s_barrier
	v_mfma_f32_16x16x32_bf16 v[62:65], v[144:147], v[176:179], v[62:65]
	v_mfma_f32_16x16x32_bf16 v[58:61], v[152:155], v[176:179], v[58:61]
	v_mfma_f32_16x16x32_bf16 v[50:53], v[144:147], v[194:197], v[50:53]
	v_mfma_f32_16x16x32_bf16 v[42:45], v[152:155], v[194:197], v[42:45]
	v_mfma_f32_16x16x32_bf16 v[34:37], v[144:147], v[202:205], v[34:37]
	v_mfma_f32_16x16x32_bf16 v[26:29], v[152:155], v[202:205], v[26:29]
	v_mfma_f32_16x16x32_bf16 v[18:21], v[144:147], v[210:213], v[18:21]
	v_mfma_f32_16x16x32_bf16 v[10:13], v[152:155], v[210:213], v[10:13]
	v_mfma_f32_16x16x32_bf16 v[62:65], v[148:151], v[190:193], v[62:65]
	v_mfma_f32_16x16x32_bf16 v[58:61], v[156:159], v[190:193], v[58:61]
	v_mfma_f32_16x16x32_bf16 v[50:53], v[148:151], v[198:201], v[50:53]
	v_mfma_f32_16x16x32_bf16 v[42:45], v[156:159], v[198:201], v[42:45]
	v_mfma_f32_16x16x32_bf16 v[34:37], v[148:151], v[206:209], v[34:37]
	v_mfma_f32_16x16x32_bf16 v[26:29], v[156:159], v[206:209], v[26:29]
	v_mfma_f32_16x16x32_bf16 v[18:21], v[148:151], v[218:221], v[18:21]
	v_mfma_f32_16x16x32_bf16 v[10:13], v[156:159], v[218:221], v[10:13]
	s_setprio 0
	s_setprio 1
	v_mfma_f32_16x16x32_bf16 v[54:57], v[160:163], v[176:179], v[54:57]
	v_mfma_f32_16x16x32_bf16 v[46:49], v[168:171], v[176:179], v[46:49]
	v_mfma_f32_16x16x32_bf16 v[38:41], v[160:163], v[194:197], v[38:41]
	v_mfma_f32_16x16x32_bf16 v[30:33], v[168:171], v[194:197], v[30:33]
	v_mfma_f32_16x16x32_bf16 v[22:25], v[160:163], v[202:205], v[22:25]
	v_mfma_f32_16x16x32_bf16 v[14:17], v[168:171], v[202:205], v[14:17]
	v_mfma_f32_16x16x32_bf16 v[6:9], v[160:163], v[210:213], v[6:9]
	v_mfma_f32_16x16x32_bf16 v[2:5], v[168:171], v[210:213], v[2:5]
	v_mfma_f32_16x16x32_bf16 v[54:57], v[164:167], v[190:193], v[54:57]
	v_mfma_f32_16x16x32_bf16 v[46:49], v[172:175], v[190:193], v[46:49]
	v_mfma_f32_16x16x32_bf16 v[38:41], v[164:167], v[198:201], v[38:41]
	v_mfma_f32_16x16x32_bf16 v[30:33], v[172:175], v[198:201], v[30:33]
	v_mfma_f32_16x16x32_bf16 v[22:25], v[164:167], v[206:209], v[22:25]
	v_mfma_f32_16x16x32_bf16 v[14:17], v[172:175], v[206:209], v[14:17]
	v_mfma_f32_16x16x32_bf16 v[6:9], v[164:167], v[218:221], v[6:9]
	v_mfma_f32_16x16x32_bf16 v[2:5], v[172:175], v[218:221], v[2:5]
	s_barrier
; #define PG8_STAGE(bufoff, gbase, voff) do { _Pragma("unroll") for (int _i = 0; _i < 2; ++_i) \
;         __builtin_amdgcn_global_load_lds((const unsigned*)((const char*)(gbase) + (voff)[_i]), (PG8_LAS unsigned*)(lds + (bufoff) + ldsw + _i * 8192), 16, 0, 0); } while (0)
; #define PG8_LDA(dst, b, h) do { _Pragma("unroll") for (int m = 0; m < 4; ++m) _Pragma("unroll") for (int k = 0; k < 2; ++k) dst[m][k] = *(const PG8_LAS bf16x8*)(lds + PG8_SA(b, h) + aoff + m * 2048 + k * 1024); } while (0)
; #define PG8_LDB(dst, b, h) do { _Pragma("unroll") for (int n = 0; n < 2; ++n) _Pragma("unroll") for (int k = 0; k < 2; ++k) dst[n][k] = *(const PG8_LAS bf16x8*)(lds + PG8_SB(b, h) + boff + n * 2048 + k * 1024); } while (0)
; #define PG8_MMA(ai, bj, At, Bt) do { __builtin_amdgcn_s_setprio(1); _Pragma("unroll") for (int m = 0; m < 4; ++m) _Pragma("unroll") for (int n = 0; n < 2; ++n) _Pragma("unroll") for (int k = 0; k < 2; ++k) \
;         acc[ai][bj][m][n] = __builtin_amdgcn_mfma_f32_16x16x32_bf16(Bt[n][k], At[m][k], acc[ai][bj][m][n], 0, 0, 0); __builtin_amdgcn_s_setprio(0); } while (0)
; #define PG8_WAIT_V(n) asm volatile("s_waitcnt vmcnt(" #n ")" ::: "memory")
; #define PG8_WAIT_L(n) asm volatile("s_waitcnt lgkmcnt(" #n ")" ::: "memory")
; #define PG8_BAR __builtin_amdgcn_s_barrier()
; #define PG8_SCHED __builtin_amdgcn_sched_barrier(0)
; template <class Epi, class Sched, bool ALIGN_EPI = false, bool SP2 = false>
; __device__ __forceinline__ void gemm_phase(PG8_LAS unsigned char* lds, const Gemm g, const Sched& S, const Epi& E) {
;     ...
;             PG8_LDB(B0, 1, 0); PG8_LDB(B1, 1, 1); PG8_SCHED; PG8_LDA(At, 1, 0); PG8_STAGE(PG8_SA(0, 1), a2 + hstep, voffA);
;             PG8_WAIT_V(8); PG8_WAIT_L(0); PG8_BAR; PG8_MMA(0, 0, At, B0); PG8_MMA(0, 1, At, B1); PG8_BAR; PG8_SCHED;
	s_setprio 0
	s_add_i32 s18, 0, 0x18000
	v_add_u32_e32 v139, s18, v180
	s_add_i32 s19, 0, 0x1c000
	ds_read_b128 v[144:147], v139
	ds_read_b128 v[148:151], v139 offset:1024
	ds_read_b128 v[152:155], v139 offset:2048
	ds_read_b128 v[156:159], v139 offset:3072
	v_add_u32_e32 v139, s19, v180
	ds_read_b128 v[160:163], v139
	ds_read_b128 v[164:167], v139 offset:1024
	ds_read_b128 v[168:171], v139 offset:2048
	ds_read_b128 v[172:175], v139 offset:3072
	s_add_u32 s10, s10, 0x100000
	s_addc_u32 s11, s11, 0
	s_mov_b32 m0, s45
	v_lshl_add_u64 v[228:229], s[10:11], 0, v[130:131]
	ds_read_b128 v[176:179], v188 offset:32768
	ds_read_b128 v[190:193], v188 offset:33792
	ds_read_b128 v[194:197], v188 offset:34816
	ds_read_b128 v[198:201], v188 offset:35840
	ds_read_b128 v[202:205], v188 offset:36864
	ds_read_b128 v[206:209], v188 offset:37888
	ds_read_b128 v[210:213], v188 offset:38912
	ds_read_b128 v[218:221], v188 offset:39936
	global_load_lds_dwordx4 v[228:229], off
	v_lshl_add_u64 v[228:229], s[10:11], 0, v[134:135]
	s_mov_b32 m0, s47
	s_nop 0
	global_load_lds_dwordx4 v[228:229], off
	s_waitcnt vmcnt(8)
	s_waitcnt lgkmcnt(0)
	s_setprio 1
	s_barrier
	v_mfma_f32_16x16x32_bf16 v[126:129], v[144:147], v[176:179], v[126:129]
	v_mfma_f32_16x16x32_bf16 v[122:125], v[152:155], v[176:179], v[122:125]
	v_mfma_f32_16x16x32_bf16 v[114:117], v[144:147], v[194:197], v[114:117]
	v_mfma_f32_16x16x32_bf16 v[106:109], v[152:155], v[194:197], v[106:109]
	v_mfma_f32_16x16x32_bf16 v[98:101], v[144:147], v[202:205], v[98:101]
	v_mfma_f32_16x16x32_bf16 v[90:93], v[152:155], v[202:205], v[90:93]
	v_mfma_f32_16x16x32_bf16 v[82:85], v[144:147], v[210:213], v[82:85]
	v_mfma_f32_16x16x32_bf16 v[74:77], v[152:155], v[210:213], v[74:77]
	v_mfma_f32_16x16x32_bf16 v[126:129], v[148:151], v[190:193], v[126:129]
	v_mfma_f32_16x16x32_bf16 v[122:125], v[156:159], v[190:193], v[122:125]
	v_mfma_f32_16x16x32_bf16 v[114:117], v[148:151], v[198:201], v[114:117]
	v_mfma_f32_16x16x32_bf16 v[106:109], v[156:159], v[198:201], v[106:109]
	v_mfma_f32_16x16x32_bf16 v[98:101], v[148:151], v[206:209], v[98:101]
	v_mfma_f32_16x16x32_bf16 v[90:93], v[156:159], v[206:209], v[90:93]
	v_mfma_f32_16x16x32_bf16 v[82:85], v[148:151], v[218:221], v[82:85]
	v_mfma_f32_16x16x32_bf16 v[74:77], v[156:159], v[218:221], v[74:77]
	s_setprio 0
	s_setprio 1
	v_mfma_f32_16x16x32_bf16 v[118:121], v[160:163], v[176:179], v[118:121]
	v_mfma_f32_16x16x32_bf16 v[110:113], v[168:171], v[176:179], v[110:113]
	v_mfma_f32_16x16x32_bf16 v[102:105], v[160:163], v[194:197], v[102:105]
	v_mfma_f32_16x16x32_bf16 v[94:97], v[168:171], v[194:197], v[94:97]
	v_mfma_f32_16x16x32_bf16 v[86:89], v[160:163], v[202:205], v[86:89]
	v_mfma_f32_16x16x32_bf16 v[78:81], v[168:171], v[202:205], v[78:81]
	v_mfma_f32_16x16x32_bf16 v[70:73], v[160:163], v[210:213], v[70:73]
	v_mfma_f32_16x16x32_bf16 v[66:69], v[168:171], v[210:213], v[66:69]
	v_mfma_f32_16x16x32_bf16 v[118:121], v[164:167], v[190:193], v[118:121]
	v_mfma_f32_16x16x32_bf16 v[110:113], v[172:175], v[190:193], v[110:113]
	v_mfma_f32_16x16x32_bf16 v[102:105], v[164:167], v[198:201], v[102:105]
	v_mfma_f32_16x16x32_bf16 v[94:97], v[172:175], v[198:201], v[94:97]
	v_mfma_f32_16x16x32_bf16 v[86:89], v[164:167], v[206:209], v[86:89]
	v_mfma_f32_16x16x32_bf16 v[78:81], v[172:175], v[206:209], v[78:81]
	v_mfma_f32_16x16x32_bf16 v[70:73], v[164:167], v[218:221], v[70:73]
	v_mfma_f32_16x16x32_bf16 v[66:69], v[172:175], v[218:221], v[66:69]
	s_barrier
; #define PG8_STAGE(bufoff, gbase, voff) do { _Pragma("unroll") for (int _i = 0; _i < 2; ++_i) \
;         __builtin_amdgcn_global_load_lds((const unsigned*)((const char*)(gbase) + (voff)[_i]), (PG8_LAS unsigned*)(lds + (bufoff) + ldsw + _i * 8192), 16, 0, 0); } while (0)
; #define PG8_LDA(dst, b, h) do { _Pragma("unroll") for (int m = 0; m < 4; ++m) _Pragma("unroll") for (int k = 0; k < 2; ++k) dst[m][k] = *(const PG8_LAS bf16x8*)(lds + PG8_SA(b, h) + aoff + m * 2048 + k * 1024); } while (0)
; #define PG8_MMA(ai, bj, At, Bt) do { __builtin_amdgcn_s_setprio(1); _Pragma("unroll") for (int m = 0; m < 4; ++m) _Pragma("unroll") for (int n = 0; n < 2; ++n) _Pragma("unroll") for (int k = 0; k < 2; ++k) \
;         acc[ai][bj][m][n] = __builtin_amdgcn_mfma_f32_16x16x32_bf16(Bt[n][k], At[m][k], acc[ai][bj][m][n], 0, 0, 0); __builtin_amdgcn_s_setprio(0); } while (0)
; #define PG8_WAIT_V(n) asm volatile("s_waitcnt vmcnt(" #n ")" ::: "memory")
; #define PG8_WAIT_L(n) asm volatile("s_waitcnt lgkmcnt(" #n ")" ::: "memory")
; #define PG8_BAR __builtin_amdgcn_s_barrier()
; #define PG8_SCHED __builtin_amdgcn_sched_barrier(0)
;     __device__ __forceinline__ void operator()(const f32x4 (&acc)[2][2][4][2], const Unit& u, int wr, int wc, int fr, int fq) const {
;         const int pn = u.pn, row0 = u.pm * BM + wr * 64 + fr, cw = wc * 32 + 8 * fq;
;         if (pn < 4)       store_tile<0, 0>(acc, Q, 1024, row0, pn * 256 + cw, qscale, nullptr, 0, fq);
; template <class Epi, class Sched, bool ALIGN_EPI = false, bool SP2 = false>
; __device__ __forceinline__ void gemm_phase(PG8_LAS unsigned char* lds, const Gemm g, const Sched& S, const Epi& E) {
;     ...
;             PG8_LDA(At, 1, 1); PG8_STAGE(PG8_SB(1, 0), b3, voffB); PG8_STAGE(PG8_SB(1, 1), b3 + hstep, voffB); PG8_STAGE(PG8_SA(1, 0), a3, voffA);
;             PG8_WAIT_V(8); PG8_WAIT_L(0); PG8_BAR; PG8_MMA(1, 0, At, B0); PG8_MMA(1, 1, At, B1); PG8_BAR; PG8_SCHED;
	s_setprio 0
	s_add_i32 s10, s18, s5
	v_lshl_add_u64 v[214:215], v[214:215], 0, s[50:51]
	s_mov_b32 m0, s10
	ds_read_b128 v[176:179], v188 offset:49152
	ds_read_b128 v[190:193], v188 offset:50176
	ds_read_b128 v[194:197], v188 offset:51200
	ds_read_b128 v[198:201], v188 offset:52224
	ds_read_b128 v[202:205], v188 offset:53248
	ds_read_b128 v[206:209], v188 offset:54272
	ds_read_b128 v[210:213], v188 offset:55296
	ds_read_b128 v[218:221], v188 offset:56320
	global_load_lds_dwordx4 v[214:215], off
	s_add_i32 m0, s10, 0x2000
	s_add_u32 s8, s8, 0x100080
	v_lshl_add_u64 v[214:215], v[222:223], 0, s[50:51]
	s_addc_u32 s9, s9, 0
	s_add_i32 s10, s19, s5
	global_load_lds_dwordx4 v[214:215], off
	v_lshl_add_u64 v[214:215], s[8:9], 0, v[132:133]
	s_mov_b32 m0, s10
	s_nop 0
	global_load_lds_dwordx4 v[214:215], off
	v_lshl_add_u64 v[214:215], s[8:9], 0, v[136:137]
	s_add_i32 m0, s10, 0x2000
	s_nop 0
	global_load_lds_dwordx4 v[214:215], off
	v_lshl_add_u64 v[214:215], v[224:225], 0, s[50:51]
	s_mov_b32 m0, s55
	s_nop 0
	global_load_lds_dwordx4 v[214:215], off
	v_lshl_add_u64 v[214:215], v[226:227], 0, s[50:51]
	s_mov_b32 m0, s57
	s_nop 0
	global_load_lds_dwordx4 v[214:215], off
	s_waitcnt vmcnt(8)
	s_waitcnt lgkmcnt(0)
	s_setprio 1
	s_barrier
	v_mfma_f32_16x16x32_bf16 v[62:65], v[144:147], v[176:179], v[62:65]
	v_mfma_f32_16x16x32_bf16 v[58:61], v[152:155], v[176:179], v[58:61]
	v_mfma_f32_16x16x32_bf16 v[50:53], v[144:147], v[194:197], v[50:53]
	v_mfma_f32_16x16x32_bf16 v[42:45], v[152:155], v[194:197], v[42:45]
	v_mfma_f32_16x16x32_bf16 v[34:37], v[144:147], v[202:205], v[34:37]
	v_mfma_f32_16x16x32_bf16 v[26:29], v[152:155], v[202:205], v[26:29]
	v_mfma_f32_16x16x32_bf16 v[18:21], v[144:147], v[210:213], v[18:21]
	v_mfma_f32_16x16x32_bf16 v[10:13], v[152:155], v[210:213], v[10:13]
	v_mfma_f32_16x16x32_bf16 v[62:65], v[148:151], v[190:193], v[62:65]
	v_mfma_f32_16x16x32_bf16 v[58:61], v[156:159], v[190:193], v[58:61]
	v_mfma_f32_16x16x32_bf16 v[50:53], v[148:151], v[198:201], v[50:53]
	v_mfma_f32_16x16x32_bf16 v[42:45], v[156:159], v[198:201], v[42:45]
	v_mfma_f32_16x16x32_bf16 v[34:37], v[148:151], v[206:209], v[34:37]
	v_mfma_f32_16x16x32_bf16 v[26:29], v[156:159], v[206:209], v[26:29]
	v_mfma_f32_16x16x32_bf16 v[18:21], v[148:151], v[218:221], v[18:21]
	v_mfma_f32_16x16x32_bf16 v[10:13], v[156:159], v[218:221], v[10:13]
	s_setprio 0
	s_setprio 1
	v_mfma_f32_16x16x32_bf16 v[54:57], v[160:163], v[176:179], v[54:57]
	v_mfma_f32_16x16x32_bf16 v[46:49], v[168:171], v[176:179], v[46:49]
	v_mfma_f32_16x16x32_bf16 v[38:41], v[160:163], v[194:197], v[38:41]
	v_mfma_f32_16x16x32_bf16 v[30:33], v[168:171], v[194:197], v[30:33]
	v_mfma_f32_16x16x32_bf16 v[22:25], v[160:163], v[202:205], v[22:25]
	v_mfma_f32_16x16x32_bf16 v[14:17], v[168:171], v[202:205], v[14:17]
	v_mfma_f32_16x16x32_bf16 v[6:9], v[160:163], v[210:213], v[6:9]
	v_mfma_f32_16x16x32_bf16 v[2:5], v[168:171], v[210:213], v[2:5]
	v_mfma_f32_16x16x32_bf16 v[54:57], v[164:167], v[190:193], v[54:57]
	v_mfma_f32_16x16x32_bf16 v[46:49], v[172:175], v[190:193], v[46:49]
	v_mfma_f32_16x16x32_bf16 v[38:41], v[164:167], v[198:201], v[38:41]
	v_mfma_f32_16x16x32_bf16 v[30:33], v[172:175], v[198:201], v[30:33]
	v_mfma_f32_16x16x32_bf16 v[22:25], v[164:167], v[206:209], v[22:25]
	v_mfma_f32_16x16x32_bf16 v[14:17], v[172:175], v[206:209], v[14:17]
	v_mfma_f32_16x16x32_bf16 v[6:9], v[164:167], v[218:221], v[6:9]
	v_mfma_f32_16x16x32_bf16 v[2:5], v[172:175], v[218:221], v[2:5]
	s_barrier
	s_setprio 0
	s_add_i32 s17, s17, 2
	s_add_u32 s6, s6, 0x100
	s_addc_u32 s7, s7, 0
	s_add_u32 s15, s15, 0x100
	s_addc_u32 s16, s16, 0
	s_cmp_gt_u32 s17, 61
	s_cbranch_scc0 .LBB0_183
	s_and_b64 vcc, exec, s[22:23]
	s_cbranch_vccnz .LBB0_188
	v_lshl_add_u32 v144, s0, 8, v1
	s_cmp_gt_i32 s40, 3
	s_mov_b64 s[0:1], -1
	s_cbranch_scc1 .LBB0_189

; __device__ __forceinline__ unsigned xb_ld(unsigned* p)              { return __hip_atomic_load(p, __ATOMIC_RELAXED, __HIP_MEMORY_SCOPE_AGENT); }
; __device__ __forceinline__ void xcd_barrier_complete(unsigned* bar, unsigned x, unsigned& nloc, unsigned& nx) {
;     const unsigned G = gridDim.x * gridDim.y * gridDim.z;
;     unsigned sum, cnt, mine, sp = 0u;
;     for (;;) {
;         sum = 0u; cnt = 0u; mine = 0u;
; #pragma unroll
;         for (unsigned j = 0; j < 16; ++j) { const unsigned c = xb_ld(&bar[XB_XCNT(j)]); sum += c; cnt += (c > 0u) ? 1u : 0u; mine = (j == x) ? c : mine; }
; __device__ __forceinline__ void xcd_barrier(const XcdBarrier& b) {
;     asm volatile("s_waitcnt vmcnt(0)" ::: "memory");
;     __syncthreads();
;     if (threadIdx.x == 0) {
;         unsigned* bar = b.bar;
;         __builtin_amdgcn_s_waitcnt(0);
;         unsigned nloc = b.st[0], nx = b.st[1];
;         if (nloc == 0u) { xcd_barrier_complete(bar, b.x, nloc, nx); b.st[0] = nloc; b.st[1] = nx; }
.LBB0_628:
	s_nop 0
	s_nop 0
	s_nop 0
	s_waitcnt lgkmcnt(0)
	s_barrier
	s_waitcnt vmcnt(0)
	s_barrier
	s_and_saveexec_b64 s[0:1], s[50:51]
	v_readlane_b32 s72, v247, 25
	v_readlane_b32 s76, v247, 21
	v_readlane_b32 s73, v247, 26
	v_readlane_b32 s77, v247, 22
	s_cbranch_execz .LBB0_680
	s_add_i32 s4, 0, 0x26020
	v_mov_b32_e32 v1, s4
	s_waitcnt vmcnt(0) expcnt(0) lgkmcnt(0)
	ds_read_b32 v3, v1
	s_add_i32 s4, 0, 0x26024
	v_mov_b32_e32 v1, s4
	ds_read_b32 v1, v1
	s_waitcnt lgkmcnt(1)
	v_cmp_ne_u32_e32 vcc, 0, v3
	s_cbranch_vccnz .LBB0_644
	v_readlane_b32 s4, v247, 0
	v_readlane_b32 s5, v247, 1
	s_load_dwordx2 s[8:9], s[4:5], 0x4
	s_add_u32 s4, s96, 0x4200
	s_addc_u32 s5, s97, 0
	s_add_u32 s6, s96, 0x4400
	s_addc_u32 s7, s97, 0
	s_waitcnt lgkmcnt(0)
	s_mul_i32 s33, s8, s60
	s_add_u32 s8, s96, 0x4500
	s_mul_i32 s33, s33, s9
	s_addc_u32 s9, s97, 0
	s_add_u32 s10, s96, 0x4600
	s_addc_u32 s11, s97, 0
	s_add_u32 s12, s96, 0x4700
	s_addc_u32 s13, s97, 0
	s_add_u32 s14, s96, 0x4800
	s_addc_u32 s15, s97, 0
	s_add_u32 s16, s96, 0x4900
	s_addc_u32 s17, s97, 0
	s_add_u32 s18, s96, 0x4a00
	s_addc_u32 s19, s97, 0
	s_add_u32 s20, s96, 0x4b00
	s_addc_u32 s21, s97, 0
	s_add_u32 s22, s96, 0x4c00
	s_addc_u32 s23, s97, 0
	s_add_u32 s24, s96, 0x4d00
	s_addc_u32 s25, s97, 0
	s_add_u32 s26, s96, 0x4e00
	s_addc_u32 s27, s97, 0
	s_add_u32 s28, s96, 0x4f00
	s_addc_u32 s29, s97, 0
	s_add_u32 s30, s96, 0x5000
	s_addc_u32 s31, s97, 0
	s_add_u32 s34, s96, 0x5100
	s_addc_u32 s35, s97, 0
	s_add_u32 s36, s96, 0x5200
	s_addc_u32 s37, s97, 0
	s_add_u32 s38, s96, 0x5300
	s_addc_u32 s39, s97, 0
	s_mov_b32 s46, 1
	v_mov_b32_e32 v17, 0
	s_branch .LBB0_632
